# G1 meta-row units run a K-loop copy without the ai=1 MFMAs (their rows 128..255 do not exist); on top of the peeled first K step
# baseline (speedup 1.0000x reference)
.LBB0_53:
	v_lshl_add_u32 v171, s48, 8, v241
	v_lshlrev_b32_e32 v171, 2, v171
	global_load_dword v164, v171, s[70:71]
	global_load_dword v165, v171, s[70:71] offset:64
	global_load_dword v166, v171, s[70:71] offset:128
	global_load_dword v167, v171, s[70:71] offset:192
	global_load_dword v246, v171, s[70:71] offset:512
	global_load_dword v247, v171, s[70:71] offset:576
	global_load_dword v248, v171, s[70:71] offset:640
	global_load_dword v249, v171, s[70:71] offset:704
	s_add_u32 s0, s4, 0x40080
	s_addc_u32 s1, s5, 0
	s_add_u32 s3, s20, 0x100
	s_addc_u32 s20, s21, 0
	s_mov_b32 s21, -2
	s_cmp_eq_u32 s48, 64
	s_cbranch_scc1 .Lg1_metak
	s_add_u32 s4, s0, 0xfffc0080
	s_addc_u32 s5, s1, -1
	s_add_i32 s36, 0, 0x10000
	v_add_u32_e32 v2, s36, v243
	ds_read_b128 v[132:135], v2
	ds_read_b128 v[136:139], v2 offset:1024
	ds_read_b128 v[140:143], v2 offset:2048
	ds_read_b128 v[144:147], v2 offset:3072
	s_cmp_eq_u32 s21, 12
	s_cselect_b32 s17, s51, s5
	s_cselect_b32 s16, s50, s4
	s_cselect_b32 s5, s7, s20
	s_cselect_b32 s4, s6, s3
	v_lshl_add_u64 v[168:169], s[0:1], 0, v[184:185]
	s_add_i32 m0, s23, 0xc000
	ds_read_b128 v[148:151], v245
	ds_read_b128 v[152:155], v245 offset:1024
	ds_read_b128 v[156:159], v245 offset:2048
	ds_read_b128 v[160:163], v245 offset:3072
	ds_read_b128 v[188:191], v245 offset:4096
	ds_read_b128 v[192:195], v245 offset:5120
	ds_read_b128 v[196:199], v245 offset:6144
	ds_read_b128 v[200:203], v245 offset:7168
	global_load_lds_dwordx4 v[168:169], off
	v_lshl_add_u64 v[168:169], s[0:1], 0, v[186:187]
	s_add_i32 m0, s23, 0xe000
	s_nop 0
	global_load_lds_dwordx4 v[168:169], off
	s_waitcnt lgkmcnt(8)
	s_barrier
	s_waitcnt lgkmcnt(0)
	s_waitcnt lgkmcnt(0)
	v_mfma_f32_16x16x32_bf16 v[128:131], v[132:135], v[148:151], 0
	v_mfma_f32_16x16x32_bf16 v[124:127], v[140:143], v[148:151], 0
	v_mfma_f32_16x16x32_bf16 v[120:123], v[132:135], v[156:159], 0
	v_mfma_f32_16x16x32_bf16 v[116:119], v[140:143], v[156:159], 0
	v_mfma_f32_16x16x32_bf16 v[112:115], v[132:135], v[188:191], 0
	v_mfma_f32_16x16x32_bf16 v[108:111], v[140:143], v[188:191], 0
	v_mfma_f32_16x16x32_bf16 v[104:107], v[132:135], v[196:199], 0
	v_mfma_f32_16x16x32_bf16 v[100:103], v[140:143], v[196:199], 0
	v_mfma_f32_16x16x32_bf16 v[128:131], v[136:139], v[152:155], v[128:131]
	v_mfma_f32_16x16x32_bf16 v[124:127], v[144:147], v[152:155], v[124:127]
	v_mfma_f32_16x16x32_bf16 v[120:123], v[136:139], v[160:163], v[120:123]
	v_mfma_f32_16x16x32_bf16 v[116:119], v[144:147], v[160:163], v[116:119]
	v_mfma_f32_16x16x32_bf16 v[112:115], v[136:139], v[192:195], v[112:115]
	v_mfma_f32_16x16x32_bf16 v[108:111], v[144:147], v[192:195], v[108:111]
	v_mfma_f32_16x16x32_bf16 v[104:107], v[136:139], v[200:203], v[104:107]
	v_mfma_f32_16x16x32_bf16 v[100:103], v[144:147], v[200:203], v[100:103]
	s_barrier
	s_add_i32 s40, 0, 0x14000
	s_add_i32 s36, s36, s18
	v_add_u32_e32 v2, s40, v243
	v_lshl_add_u64 v[168:169], s[4:5], 0, v[172:173]
	s_mov_b32 m0, s36
	ds_read_b128 v[204:207], v2
	ds_read_b128 v[208:211], v2 offset:1024
	ds_read_b128 v[234:237], v2 offset:2048
	ds_read_b128 v[220:223], v2 offset:3072
	global_load_lds_dwordx4 v[168:169], off
	v_lshl_add_u64 v[238:239], s[4:5], 0, v[176:177]
	s_add_i32 m0, s36, 0x2000
	s_nop 0
	global_load_lds_dwordx4 v[238:239], off
	s_barrier
	s_waitcnt lgkmcnt(0)
	s_waitcnt lgkmcnt(0)
	v_mfma_f32_16x16x32_bf16 v[64:67], v[204:207], v[148:151], 0
	v_mfma_f32_16x16x32_bf16 v[60:63], v[234:237], v[148:151], 0
	v_mfma_f32_16x16x32_bf16 v[56:59], v[204:207], v[156:159], 0
	v_mfma_f32_16x16x32_bf16 v[52:55], v[234:237], v[156:159], 0
	v_mfma_f32_16x16x32_bf16 v[48:51], v[204:207], v[188:191], 0
	v_mfma_f32_16x16x32_bf16 v[44:47], v[234:237], v[188:191], 0
	v_mfma_f32_16x16x32_bf16 v[40:43], v[204:207], v[196:199], 0
	v_mfma_f32_16x16x32_bf16 v[36:39], v[234:237], v[196:199], 0
	v_mfma_f32_16x16x32_bf16 v[64:67], v[208:211], v[152:155], v[64:67]
	v_mfma_f32_16x16x32_bf16 v[60:63], v[220:223], v[152:155], v[60:63]
	v_mfma_f32_16x16x32_bf16 v[56:59], v[208:211], v[160:163], v[56:59]
	v_mfma_f32_16x16x32_bf16 v[52:55], v[220:223], v[160:163], v[52:55]
	v_mfma_f32_16x16x32_bf16 v[48:51], v[208:211], v[192:195], v[48:51]
	v_mfma_f32_16x16x32_bf16 v[44:47], v[220:223], v[192:195], v[44:47]
	v_mfma_f32_16x16x32_bf16 v[40:43], v[208:211], v[200:203], v[40:43]
	v_mfma_f32_16x16x32_bf16 v[36:39], v[220:223], v[200:203], v[36:39]
	s_mov_b32 m0, s23
	v_lshl_add_u64 v[214:215], s[16:17], 0, v[0:1]
	s_barrier
	ds_read_b128 v[148:151], v245 offset:16384
	ds_read_b128 v[152:155], v245 offset:17408
	ds_read_b128 v[156:159], v245 offset:18432
	ds_read_b128 v[160:163], v245 offset:19456
	ds_read_b128 v[188:191], v245 offset:20480
	ds_read_b128 v[192:195], v245 offset:21504
	ds_read_b128 v[196:199], v245 offset:22528
	ds_read_b128 v[200:203], v245 offset:23552
	global_load_lds_dwordx4 v[214:215], off
	v_lshl_add_u64 v[224:225], s[16:17], 0, v[174:175]
	s_mov_b32 m0, s26
	s_nop 0
	global_load_lds_dwordx4 v[224:225], off
	s_barrier
	s_waitcnt lgkmcnt(0)
	s_waitcnt lgkmcnt(0)
	v_mfma_f32_16x16x32_bf16 v[96:99], v[132:135], v[148:151], 0
	v_mfma_f32_16x16x32_bf16 v[92:95], v[140:143], v[148:151], 0
	v_mfma_f32_16x16x32_bf16 v[88:91], v[132:135], v[156:159], 0
	v_mfma_f32_16x16x32_bf16 v[84:87], v[140:143], v[156:159], 0
	v_mfma_f32_16x16x32_bf16 v[80:83], v[132:135], v[188:191], 0
	v_mfma_f32_16x16x32_bf16 v[76:79], v[140:143], v[188:191], 0
	v_mfma_f32_16x16x32_bf16 v[72:75], v[132:135], v[196:199], 0
	v_mfma_f32_16x16x32_bf16 v[68:71], v[140:143], v[196:199], 0
	v_mfma_f32_16x16x32_bf16 v[96:99], v[136:139], v[152:155], v[96:99]
	v_mfma_f32_16x16x32_bf16 v[92:95], v[144:147], v[152:155], v[92:95]
	v_mfma_f32_16x16x32_bf16 v[88:91], v[136:139], v[160:163], v[88:91]
	v_mfma_f32_16x16x32_bf16 v[84:87], v[144:147], v[160:163], v[84:87]
	v_mfma_f32_16x16x32_bf16 v[80:83], v[136:139], v[192:195], v[80:83]
	v_mfma_f32_16x16x32_bf16 v[76:79], v[144:147], v[192:195], v[76:79]
	v_mfma_f32_16x16x32_bf16 v[72:75], v[136:139], v[200:203], v[72:75]
	v_mfma_f32_16x16x32_bf16 v[68:71], v[144:147], v[200:203], v[68:71]
	s_barrier
	s_add_u32 s36, s4, 0x40000
	s_addc_u32 s37, s5, 0
	s_add_i32 s40, s40, s18
	v_lshl_add_u64 v[132:133], s[36:37], 0, v[172:173]
	s_mov_b32 m0, s40
	s_nop 0
	global_load_lds_dwordx4 v[132:133], off
	v_lshl_add_u64 v[132:133], s[36:37], 0, v[176:177]
	s_add_i32 m0, s40, 0x2000
	s_nop 0
	global_load_lds_dwordx4 v[132:133], off
	s_waitcnt vmcnt(6)
	s_barrier
	v_mfma_f32_16x16x32_bf16 v[32:35], v[204:207], v[148:151], 0
	v_mfma_f32_16x16x32_bf16 v[28:31], v[234:237], v[148:151], 0
	v_mfma_f32_16x16x32_bf16 v[24:27], v[204:207], v[156:159], 0
	v_mfma_f32_16x16x32_bf16 v[20:23], v[234:237], v[156:159], 0
	v_mfma_f32_16x16x32_bf16 v[16:19], v[204:207], v[188:191], 0
	v_mfma_f32_16x16x32_bf16 v[12:15], v[234:237], v[188:191], 0
	v_mfma_f32_16x16x32_bf16 v[8:11], v[204:207], v[196:199], 0
	v_mfma_f32_16x16x32_bf16 v[4:7], v[234:237], v[196:199], 0
	v_mfma_f32_16x16x32_bf16 v[32:35], v[208:211], v[152:155], v[32:35]
	v_mfma_f32_16x16x32_bf16 v[28:31], v[220:223], v[152:155], v[28:31]
	v_mfma_f32_16x16x32_bf16 v[24:27], v[208:211], v[160:163], v[24:27]
	v_mfma_f32_16x16x32_bf16 v[20:23], v[220:223], v[160:163], v[20:23]
	v_mfma_f32_16x16x32_bf16 v[16:19], v[208:211], v[192:195], v[16:19]
	v_mfma_f32_16x16x32_bf16 v[12:15], v[220:223], v[192:195], v[12:15]
	v_mfma_f32_16x16x32_bf16 v[8:11], v[208:211], v[200:203], v[8:11]
	v_mfma_f32_16x16x32_bf16 v[4:7], v[220:223], v[200:203], v[4:7]
	s_add_i32 s36, 0, 0x18000
	v_add_u32_e32 v2, s36, v243
	s_barrier
	ds_read_b128 v[132:135], v2
	ds_read_b128 v[136:139], v2 offset:1024
	ds_read_b128 v[140:143], v2 offset:2048
	ds_read_b128 v[144:147], v2 offset:3072
	s_add_u32 s16, s16, 0x40000
	s_addc_u32 s17, s17, 0
	s_mov_b32 m0, s27
	v_lshl_add_u64 v[204:205], s[16:17], 0, v[0:1]
	ds_read_b128 v[148:151], v245 offset:32768
	ds_read_b128 v[152:155], v245 offset:33792
	ds_read_b128 v[156:159], v245 offset:34816
	ds_read_b128 v[160:163], v245 offset:35840
	ds_read_b128 v[188:191], v245 offset:36864
	ds_read_b128 v[192:195], v245 offset:37888
	ds_read_b128 v[196:199], v245 offset:38912
	ds_read_b128 v[200:203], v245 offset:39936
	global_load_lds_dwordx4 v[204:205], off
	v_lshl_add_u64 v[204:205], s[16:17], 0, v[174:175]
	s_mov_b32 m0, s30
	s_nop 0
	global_load_lds_dwordx4 v[204:205], off
	s_waitcnt lgkmcnt(8)
	s_barrier
	s_waitcnt lgkmcnt(0)
	s_waitcnt lgkmcnt(0)
	v_mfma_f32_16x16x32_bf16 v[128:131], v[132:135], v[148:151], v[128:131]
	v_mfma_f32_16x16x32_bf16 v[124:127], v[140:143], v[148:151], v[124:127]
	v_mfma_f32_16x16x32_bf16 v[120:123], v[132:135], v[156:159], v[120:123]
	v_mfma_f32_16x16x32_bf16 v[116:119], v[140:143], v[156:159], v[116:119]
	v_mfma_f32_16x16x32_bf16 v[112:115], v[132:135], v[188:191], v[112:115]
	v_mfma_f32_16x16x32_bf16 v[108:111], v[140:143], v[188:191], v[108:111]
	v_mfma_f32_16x16x32_bf16 v[104:107], v[132:135], v[196:199], v[104:107]
	v_mfma_f32_16x16x32_bf16 v[100:103], v[140:143], v[196:199], v[100:103]
	v_mfma_f32_16x16x32_bf16 v[128:131], v[136:139], v[152:155], v[128:131]
	v_mfma_f32_16x16x32_bf16 v[124:127], v[144:147], v[152:155], v[124:127]
	v_mfma_f32_16x16x32_bf16 v[120:123], v[136:139], v[160:163], v[120:123]
	v_mfma_f32_16x16x32_bf16 v[116:119], v[144:147], v[160:163], v[116:119]
	v_mfma_f32_16x16x32_bf16 v[112:115], v[136:139], v[192:195], v[112:115]
	v_mfma_f32_16x16x32_bf16 v[108:111], v[144:147], v[192:195], v[108:111]
	v_mfma_f32_16x16x32_bf16 v[104:107], v[136:139], v[200:203], v[104:107]
	v_mfma_f32_16x16x32_bf16 v[100:103], v[144:147], v[200:203], v[100:103]
	s_barrier
	s_add_i32 s16, 0, 0x1c000
	s_add_i32 s17, s36, s18
	v_add_u32_e32 v2, s16, v243
	v_lshl_add_u64 v[168:169], v[168:169], 0, s[28:29]
	s_mov_b32 m0, s17
	ds_read_b128 v[204:207], v2
	ds_read_b128 v[208:211], v2 offset:1024
	ds_read_b128 v[220:223], v2 offset:2048
	ds_read_b128 v[234:237], v2 offset:3072
	global_load_lds_dwordx4 v[168:169], off
	v_lshl_add_u64 v[168:169], v[238:239], 0, s[28:29]
	s_add_i32 m0, s17, 0x2000
	s_nop 0
	global_load_lds_dwordx4 v[168:169], off
	s_barrier
	s_waitcnt lgkmcnt(0)
	s_waitcnt lgkmcnt(0)
	v_mfma_f32_16x16x32_bf16 v[64:67], v[204:207], v[148:151], v[64:67]
	v_mfma_f32_16x16x32_bf16 v[60:63], v[220:223], v[148:151], v[60:63]
	v_mfma_f32_16x16x32_bf16 v[56:59], v[204:207], v[156:159], v[56:59]
	v_mfma_f32_16x16x32_bf16 v[52:55], v[220:223], v[156:159], v[52:55]
	v_mfma_f32_16x16x32_bf16 v[48:51], v[204:207], v[188:191], v[48:51]
	v_mfma_f32_16x16x32_bf16 v[44:47], v[220:223], v[188:191], v[44:47]
	v_mfma_f32_16x16x32_bf16 v[40:43], v[204:207], v[196:199], v[40:43]
	v_mfma_f32_16x16x32_bf16 v[36:39], v[220:223], v[196:199], v[36:39]
	v_mfma_f32_16x16x32_bf16 v[64:67], v[208:211], v[152:155], v[64:67]
	v_mfma_f32_16x16x32_bf16 v[60:63], v[234:237], v[152:155], v[60:63]
	v_mfma_f32_16x16x32_bf16 v[56:59], v[208:211], v[160:163], v[56:59]
	v_mfma_f32_16x16x32_bf16 v[52:55], v[234:237], v[160:163], v[52:55]
	v_mfma_f32_16x16x32_bf16 v[48:51], v[208:211], v[192:195], v[48:51]
	v_mfma_f32_16x16x32_bf16 v[44:47], v[234:237], v[192:195], v[44:47]
	v_mfma_f32_16x16x32_bf16 v[40:43], v[208:211], v[200:203], v[40:43]
	v_mfma_f32_16x16x32_bf16 v[36:39], v[234:237], v[200:203], v[36:39]
	s_mov_b32 m0, s76
	v_lshl_add_u64 v[168:169], v[214:215], 0, s[28:29]
	s_barrier
	ds_read_b128 v[148:151], v245 offset:49152
	ds_read_b128 v[152:155], v245 offset:50176
	ds_read_b128 v[156:159], v245 offset:51200
	ds_read_b128 v[160:163], v245 offset:52224
	ds_read_b128 v[188:191], v245 offset:53248
	ds_read_b128 v[192:195], v245 offset:54272
	ds_read_b128 v[196:199], v245 offset:55296
	ds_read_b128 v[200:203], v245 offset:56320
	global_load_lds_dwordx4 v[168:169], off
	v_lshl_add_u64 v[168:169], v[224:225], 0, s[28:29]
	s_mov_b32 m0, s77
	s_nop 0
	global_load_lds_dwordx4 v[168:169], off
	s_barrier
	s_waitcnt lgkmcnt(0)
	s_waitcnt lgkmcnt(0)
	v_mfma_f32_16x16x32_bf16 v[96:99], v[132:135], v[148:151], v[96:99]
	v_mfma_f32_16x16x32_bf16 v[92:95], v[140:143], v[148:151], v[92:95]
	v_mfma_f32_16x16x32_bf16 v[88:91], v[132:135], v[156:159], v[88:91]
	v_mfma_f32_16x16x32_bf16 v[84:87], v[140:143], v[156:159], v[84:87]
	v_mfma_f32_16x16x32_bf16 v[80:83], v[132:135], v[188:191], v[80:83]
	v_mfma_f32_16x16x32_bf16 v[76:79], v[140:143], v[188:191], v[76:79]
	v_mfma_f32_16x16x32_bf16 v[72:75], v[132:135], v[196:199], v[72:75]
	v_mfma_f32_16x16x32_bf16 v[68:71], v[140:143], v[196:199], v[68:71]
	v_mfma_f32_16x16x32_bf16 v[96:99], v[136:139], v[152:155], v[96:99]
	v_mfma_f32_16x16x32_bf16 v[92:95], v[144:147], v[152:155], v[92:95]
	v_mfma_f32_16x16x32_bf16 v[88:91], v[136:139], v[160:163], v[88:91]
	v_mfma_f32_16x16x32_bf16 v[84:87], v[144:147], v[160:163], v[84:87]
	v_mfma_f32_16x16x32_bf16 v[80:83], v[136:139], v[192:195], v[80:83]
	v_mfma_f32_16x16x32_bf16 v[76:79], v[144:147], v[192:195], v[76:79]
	v_mfma_f32_16x16x32_bf16 v[72:75], v[136:139], v[200:203], v[72:75]
	v_mfma_f32_16x16x32_bf16 v[68:71], v[144:147], v[200:203], v[68:71]
	s_barrier
	s_add_u32 s4, s4, 0x40080
	s_addc_u32 s5, s5, 0
	s_add_i32 s16, s16, s18
	v_lshl_add_u64 v[132:133], s[4:5], 0, v[172:173]
	s_mov_b32 m0, s16
	s_nop 0
	global_load_lds_dwordx4 v[132:133], off
	v_lshl_add_u64 v[132:133], s[4:5], 0, v[176:177]
	s_add_i32 m0, s16, 0x2000
	s_nop 0
	global_load_lds_dwordx4 v[132:133], off
	s_waitcnt vmcnt(6)
	s_barrier
	v_mfma_f32_16x16x32_bf16 v[32:35], v[204:207], v[148:151], v[32:35]
	v_mfma_f32_16x16x32_bf16 v[28:31], v[220:223], v[148:151], v[28:31]
	v_mfma_f32_16x16x32_bf16 v[24:27], v[204:207], v[156:159], v[24:27]
	v_mfma_f32_16x16x32_bf16 v[20:23], v[220:223], v[156:159], v[20:23]
	v_mfma_f32_16x16x32_bf16 v[16:19], v[204:207], v[188:191], v[16:19]
	v_mfma_f32_16x16x32_bf16 v[12:15], v[220:223], v[188:191], v[12:15]
	v_mfma_f32_16x16x32_bf16 v[8:11], v[204:207], v[196:199], v[8:11]
	v_mfma_f32_16x16x32_bf16 v[4:7], v[220:223], v[196:199], v[4:7]
	v_mfma_f32_16x16x32_bf16 v[32:35], v[208:211], v[152:155], v[32:35]
	v_mfma_f32_16x16x32_bf16 v[28:31], v[234:237], v[152:155], v[28:31]
	v_mfma_f32_16x16x32_bf16 v[24:27], v[208:211], v[160:163], v[24:27]
	v_mfma_f32_16x16x32_bf16 v[20:23], v[234:237], v[160:163], v[20:23]
	v_mfma_f32_16x16x32_bf16 v[16:19], v[208:211], v[192:195], v[16:19]
	v_mfma_f32_16x16x32_bf16 v[12:15], v[234:237], v[192:195], v[12:15]
	v_mfma_f32_16x16x32_bf16 v[8:11], v[208:211], v[200:203], v[8:11]
	v_mfma_f32_16x16x32_bf16 v[4:7], v[234:237], v[200:203], v[4:7]
	s_add_i32 s21, s21, 2
	s_add_u32 s0, s0, 0x100
	s_addc_u32 s1, s1, 0
	s_add_u32 s3, s3, 0x100
	s_addc_u32 s20, s20, 0
	s_cmp_gt_u32 s21, 13
	s_barrier
.LBB0_54:
	s_add_u32 s4, s0, 0xfffc0080
	s_addc_u32 s5, s1, -1
	s_add_i32 s36, 0, 0x10000
	v_add_u32_e32 v2, s36, v243
	ds_read_b128 v[132:135], v2
	ds_read_b128 v[136:139], v2 offset:1024
	ds_read_b128 v[140:143], v2 offset:2048
	ds_read_b128 v[144:147], v2 offset:3072
	s_cmp_eq_u32 s21, 12
	s_cselect_b32 s17, s51, s5
	s_cselect_b32 s16, s50, s4
	s_cselect_b32 s5, s7, s20
	s_cselect_b32 s4, s6, s3
	v_lshl_add_u64 v[168:169], s[0:1], 0, v[184:185]
	s_add_i32 m0, s23, 0xc000
	ds_read_b128 v[148:151], v245
	ds_read_b128 v[152:155], v245 offset:1024
	ds_read_b128 v[156:159], v245 offset:2048
	ds_read_b128 v[160:163], v245 offset:3072
	ds_read_b128 v[188:191], v245 offset:4096
	ds_read_b128 v[192:195], v245 offset:5120
	ds_read_b128 v[196:199], v245 offset:6144
	ds_read_b128 v[200:203], v245 offset:7168
	global_load_lds_dwordx4 v[168:169], off
	v_lshl_add_u64 v[168:169], s[0:1], 0, v[186:187]
	s_add_i32 m0, s23, 0xe000
	s_nop 0
	global_load_lds_dwordx4 v[168:169], off
	s_waitcnt lgkmcnt(8)
	s_barrier
	s_waitcnt lgkmcnt(0)
	s_waitcnt lgkmcnt(0)
	v_mfma_f32_16x16x32_bf16 v[128:131], v[132:135], v[148:151], v[128:131]
	v_mfma_f32_16x16x32_bf16 v[124:127], v[140:143], v[148:151], v[124:127]
	v_mfma_f32_16x16x32_bf16 v[120:123], v[132:135], v[156:159], v[120:123]
	v_mfma_f32_16x16x32_bf16 v[116:119], v[140:143], v[156:159], v[116:119]
	v_mfma_f32_16x16x32_bf16 v[112:115], v[132:135], v[188:191], v[112:115]
	v_mfma_f32_16x16x32_bf16 v[108:111], v[140:143], v[188:191], v[108:111]
	v_mfma_f32_16x16x32_bf16 v[104:107], v[132:135], v[196:199], v[104:107]
	v_mfma_f32_16x16x32_bf16 v[100:103], v[140:143], v[196:199], v[100:103]
	v_mfma_f32_16x16x32_bf16 v[128:131], v[136:139], v[152:155], v[128:131]
	v_mfma_f32_16x16x32_bf16 v[124:127], v[144:147], v[152:155], v[124:127]
	v_mfma_f32_16x16x32_bf16 v[120:123], v[136:139], v[160:163], v[120:123]
	v_mfma_f32_16x16x32_bf16 v[116:119], v[144:147], v[160:163], v[116:119]
	v_mfma_f32_16x16x32_bf16 v[112:115], v[136:139], v[192:195], v[112:115]
	v_mfma_f32_16x16x32_bf16 v[108:111], v[144:147], v[192:195], v[108:111]
	v_mfma_f32_16x16x32_bf16 v[104:107], v[136:139], v[200:203], v[104:107]
	v_mfma_f32_16x16x32_bf16 v[100:103], v[144:147], v[200:203], v[100:103]
	s_barrier
	s_add_i32 s40, 0, 0x14000
	s_add_i32 s36, s36, s18
	v_add_u32_e32 v2, s40, v243
	v_lshl_add_u64 v[168:169], s[4:5], 0, v[172:173]
	s_mov_b32 m0, s36
	ds_read_b128 v[204:207], v2
	ds_read_b128 v[208:211], v2 offset:1024
	ds_read_b128 v[234:237], v2 offset:2048
	ds_read_b128 v[220:223], v2 offset:3072
	global_load_lds_dwordx4 v[168:169], off
	v_lshl_add_u64 v[238:239], s[4:5], 0, v[176:177]
	s_add_i32 m0, s36, 0x2000
	s_nop 0
	global_load_lds_dwordx4 v[238:239], off
	s_barrier
	s_waitcnt lgkmcnt(0)
	s_waitcnt lgkmcnt(0)
	v_mfma_f32_16x16x32_bf16 v[64:67], v[204:207], v[148:151], v[64:67]
	v_mfma_f32_16x16x32_bf16 v[60:63], v[234:237], v[148:151], v[60:63]
	v_mfma_f32_16x16x32_bf16 v[56:59], v[204:207], v[156:159], v[56:59]
	v_mfma_f32_16x16x32_bf16 v[52:55], v[234:237], v[156:159], v[52:55]
	v_mfma_f32_16x16x32_bf16 v[48:51], v[204:207], v[188:191], v[48:51]
	v_mfma_f32_16x16x32_bf16 v[44:47], v[234:237], v[188:191], v[44:47]
	v_mfma_f32_16x16x32_bf16 v[40:43], v[204:207], v[196:199], v[40:43]
	v_mfma_f32_16x16x32_bf16 v[36:39], v[234:237], v[196:199], v[36:39]
	v_mfma_f32_16x16x32_bf16 v[64:67], v[208:211], v[152:155], v[64:67]
	v_mfma_f32_16x16x32_bf16 v[60:63], v[220:223], v[152:155], v[60:63]
	v_mfma_f32_16x16x32_bf16 v[56:59], v[208:211], v[160:163], v[56:59]
	v_mfma_f32_16x16x32_bf16 v[52:55], v[220:223], v[160:163], v[52:55]
	v_mfma_f32_16x16x32_bf16 v[48:51], v[208:211], v[192:195], v[48:51]
	v_mfma_f32_16x16x32_bf16 v[44:47], v[220:223], v[192:195], v[44:47]
	v_mfma_f32_16x16x32_bf16 v[40:43], v[208:211], v[200:203], v[40:43]
	v_mfma_f32_16x16x32_bf16 v[36:39], v[220:223], v[200:203], v[36:39]
	s_mov_b32 m0, s23
	v_lshl_add_u64 v[214:215], s[16:17], 0, v[0:1]
	s_barrier
	ds_read_b128 v[148:151], v245 offset:16384
	ds_read_b128 v[152:155], v245 offset:17408
	ds_read_b128 v[156:159], v245 offset:18432
	ds_read_b128 v[160:163], v245 offset:19456
	ds_read_b128 v[188:191], v245 offset:20480
	ds_read_b128 v[192:195], v245 offset:21504
	ds_read_b128 v[196:199], v245 offset:22528
	ds_read_b128 v[200:203], v245 offset:23552
	global_load_lds_dwordx4 v[214:215], off
	v_lshl_add_u64 v[224:225], s[16:17], 0, v[174:175]
	s_mov_b32 m0, s26
	s_nop 0
	global_load_lds_dwordx4 v[224:225], off
	s_barrier
	s_waitcnt lgkmcnt(0)
	s_waitcnt lgkmcnt(0)
	v_mfma_f32_16x16x32_bf16 v[96:99], v[132:135], v[148:151], v[96:99]
	v_mfma_f32_16x16x32_bf16 v[92:95], v[140:143], v[148:151], v[92:95]
	v_mfma_f32_16x16x32_bf16 v[88:91], v[132:135], v[156:159], v[88:91]
	v_mfma_f32_16x16x32_bf16 v[84:87], v[140:143], v[156:159], v[84:87]
	v_mfma_f32_16x16x32_bf16 v[80:83], v[132:135], v[188:191], v[80:83]
	v_mfma_f32_16x16x32_bf16 v[76:79], v[140:143], v[188:191], v[76:79]
	v_mfma_f32_16x16x32_bf16 v[72:75], v[132:135], v[196:199], v[72:75]
	v_mfma_f32_16x16x32_bf16 v[68:71], v[140:143], v[196:199], v[68:71]
	v_mfma_f32_16x16x32_bf16 v[96:99], v[136:139], v[152:155], v[96:99]
	v_mfma_f32_16x16x32_bf16 v[92:95], v[144:147], v[152:155], v[92:95]
	v_mfma_f32_16x16x32_bf16 v[88:91], v[136:139], v[160:163], v[88:91]
	v_mfma_f32_16x16x32_bf16 v[84:87], v[144:147], v[160:163], v[84:87]
	v_mfma_f32_16x16x32_bf16 v[80:83], v[136:139], v[192:195], v[80:83]
	v_mfma_f32_16x16x32_bf16 v[76:79], v[144:147], v[192:195], v[76:79]
	v_mfma_f32_16x16x32_bf16 v[72:75], v[136:139], v[200:203], v[72:75]
	v_mfma_f32_16x16x32_bf16 v[68:71], v[144:147], v[200:203], v[68:71]
	s_barrier
	s_add_u32 s36, s4, 0x40000
	s_addc_u32 s37, s5, 0
	s_add_i32 s40, s40, s18
	v_lshl_add_u64 v[132:133], s[36:37], 0, v[172:173]
	s_mov_b32 m0, s40
	s_nop 0
	global_load_lds_dwordx4 v[132:133], off
	v_lshl_add_u64 v[132:133], s[36:37], 0, v[176:177]
	s_add_i32 m0, s40, 0x2000
	s_nop 0
	global_load_lds_dwordx4 v[132:133], off
	s_waitcnt vmcnt(6)
	s_barrier
	v_mfma_f32_16x16x32_bf16 v[32:35], v[204:207], v[148:151], v[32:35]
	v_mfma_f32_16x16x32_bf16 v[28:31], v[234:237], v[148:151], v[28:31]
	v_mfma_f32_16x16x32_bf16 v[24:27], v[204:207], v[156:159], v[24:27]
	v_mfma_f32_16x16x32_bf16 v[20:23], v[234:237], v[156:159], v[20:23]
	v_mfma_f32_16x16x32_bf16 v[16:19], v[204:207], v[188:191], v[16:19]
	v_mfma_f32_16x16x32_bf16 v[12:15], v[234:237], v[188:191], v[12:15]
	v_mfma_f32_16x16x32_bf16 v[8:11], v[204:207], v[196:199], v[8:11]
	v_mfma_f32_16x16x32_bf16 v[4:7], v[234:237], v[196:199], v[4:7]
	v_mfma_f32_16x16x32_bf16 v[32:35], v[208:211], v[152:155], v[32:35]
	v_mfma_f32_16x16x32_bf16 v[28:31], v[220:223], v[152:155], v[28:31]
	v_mfma_f32_16x16x32_bf16 v[24:27], v[208:211], v[160:163], v[24:27]
	v_mfma_f32_16x16x32_bf16 v[20:23], v[220:223], v[160:163], v[20:23]
	v_mfma_f32_16x16x32_bf16 v[16:19], v[208:211], v[192:195], v[16:19]
	v_mfma_f32_16x16x32_bf16 v[12:15], v[220:223], v[192:195], v[12:15]
	v_mfma_f32_16x16x32_bf16 v[8:11], v[208:211], v[200:203], v[8:11]
	v_mfma_f32_16x16x32_bf16 v[4:7], v[220:223], v[200:203], v[4:7]
	s_add_i32 s36, 0, 0x18000
	v_add_u32_e32 v2, s36, v243
	s_barrier
	ds_read_b128 v[132:135], v2
	ds_read_b128 v[136:139], v2 offset:1024
	ds_read_b128 v[140:143], v2 offset:2048
	ds_read_b128 v[144:147], v2 offset:3072
	s_add_u32 s16, s16, 0x40000
	s_addc_u32 s17, s17, 0
	s_mov_b32 m0, s27
	v_lshl_add_u64 v[204:205], s[16:17], 0, v[0:1]
	ds_read_b128 v[148:151], v245 offset:32768
	ds_read_b128 v[152:155], v245 offset:33792
	ds_read_b128 v[156:159], v245 offset:34816
	ds_read_b128 v[160:163], v245 offset:35840
	ds_read_b128 v[188:191], v245 offset:36864
	ds_read_b128 v[192:195], v245 offset:37888
	ds_read_b128 v[196:199], v245 offset:38912
	ds_read_b128 v[200:203], v245 offset:39936
	global_load_lds_dwordx4 v[204:205], off
	v_lshl_add_u64 v[204:205], s[16:17], 0, v[174:175]
	s_mov_b32 m0, s30
	s_nop 0
	global_load_lds_dwordx4 v[204:205], off
	s_waitcnt lgkmcnt(8)
	s_barrier
	s_waitcnt lgkmcnt(0)
	s_waitcnt lgkmcnt(0)
	v_mfma_f32_16x16x32_bf16 v[128:131], v[132:135], v[148:151], v[128:131]
	v_mfma_f32_16x16x32_bf16 v[124:127], v[140:143], v[148:151], v[124:127]
	v_mfma_f32_16x16x32_bf16 v[120:123], v[132:135], v[156:159], v[120:123]
	v_mfma_f32_16x16x32_bf16 v[116:119], v[140:143], v[156:159], v[116:119]
	v_mfma_f32_16x16x32_bf16 v[112:115], v[132:135], v[188:191], v[112:115]
	v_mfma_f32_16x16x32_bf16 v[108:111], v[140:143], v[188:191], v[108:111]
	v_mfma_f32_16x16x32_bf16 v[104:107], v[132:135], v[196:199], v[104:107]
	v_mfma_f32_16x16x32_bf16 v[100:103], v[140:143], v[196:199], v[100:103]
	v_mfma_f32_16x16x32_bf16 v[128:131], v[136:139], v[152:155], v[128:131]
	v_mfma_f32_16x16x32_bf16 v[124:127], v[144:147], v[152:155], v[124:127]
	v_mfma_f32_16x16x32_bf16 v[120:123], v[136:139], v[160:163], v[120:123]
	v_mfma_f32_16x16x32_bf16 v[116:119], v[144:147], v[160:163], v[116:119]
	v_mfma_f32_16x16x32_bf16 v[112:115], v[136:139], v[192:195], v[112:115]
	v_mfma_f32_16x16x32_bf16 v[108:111], v[144:147], v[192:195], v[108:111]
	v_mfma_f32_16x16x32_bf16 v[104:107], v[136:139], v[200:203], v[104:107]
	v_mfma_f32_16x16x32_bf16 v[100:103], v[144:147], v[200:203], v[100:103]
	s_barrier
	s_add_i32 s16, 0, 0x1c000
	s_add_i32 s17, s36, s18
	v_add_u32_e32 v2, s16, v243
	v_lshl_add_u64 v[168:169], v[168:169], 0, s[28:29]
	s_mov_b32 m0, s17
	ds_read_b128 v[204:207], v2
	ds_read_b128 v[208:211], v2 offset:1024
	ds_read_b128 v[220:223], v2 offset:2048
	ds_read_b128 v[234:237], v2 offset:3072
	global_load_lds_dwordx4 v[168:169], off
	v_lshl_add_u64 v[168:169], v[238:239], 0, s[28:29]
	s_add_i32 m0, s17, 0x2000
	s_nop 0
	global_load_lds_dwordx4 v[168:169], off
	s_barrier
	s_waitcnt lgkmcnt(0)
	s_waitcnt lgkmcnt(0)
	v_mfma_f32_16x16x32_bf16 v[64:67], v[204:207], v[148:151], v[64:67]
	v_mfma_f32_16x16x32_bf16 v[60:63], v[220:223], v[148:151], v[60:63]
	v_mfma_f32_16x16x32_bf16 v[56:59], v[204:207], v[156:159], v[56:59]
	v_mfma_f32_16x16x32_bf16 v[52:55], v[220:223], v[156:159], v[52:55]
	v_mfma_f32_16x16x32_bf16 v[48:51], v[204:207], v[188:191], v[48:51]
	v_mfma_f32_16x16x32_bf16 v[44:47], v[220:223], v[188:191], v[44:47]
	v_mfma_f32_16x16x32_bf16 v[40:43], v[204:207], v[196:199], v[40:43]
	v_mfma_f32_16x16x32_bf16 v[36:39], v[220:223], v[196:199], v[36:39]
	v_mfma_f32_16x16x32_bf16 v[64:67], v[208:211], v[152:155], v[64:67]
	v_mfma_f32_16x16x32_bf16 v[60:63], v[234:237], v[152:155], v[60:63]
	v_mfma_f32_16x16x32_bf16 v[56:59], v[208:211], v[160:163], v[56:59]
	v_mfma_f32_16x16x32_bf16 v[52:55], v[234:237], v[160:163], v[52:55]
	v_mfma_f32_16x16x32_bf16 v[48:51], v[208:211], v[192:195], v[48:51]
	v_mfma_f32_16x16x32_bf16 v[44:47], v[234:237], v[192:195], v[44:47]
	v_mfma_f32_16x16x32_bf16 v[40:43], v[208:211], v[200:203], v[40:43]
	v_mfma_f32_16x16x32_bf16 v[36:39], v[234:237], v[200:203], v[36:39]
	s_mov_b32 m0, s76
	v_lshl_add_u64 v[168:169], v[214:215], 0, s[28:29]
	s_barrier
	ds_read_b128 v[148:151], v245 offset:49152
	ds_read_b128 v[152:155], v245 offset:50176
	ds_read_b128 v[156:159], v245 offset:51200
	ds_read_b128 v[160:163], v245 offset:52224
	ds_read_b128 v[188:191], v245 offset:53248
	ds_read_b128 v[192:195], v245 offset:54272
	ds_read_b128 v[196:199], v245 offset:55296
	ds_read_b128 v[200:203], v245 offset:56320
	global_load_lds_dwordx4 v[168:169], off
	v_lshl_add_u64 v[168:169], v[224:225], 0, s[28:29]
	s_mov_b32 m0, s77
	s_nop 0
	global_load_lds_dwordx4 v[168:169], off
	s_barrier
	s_waitcnt lgkmcnt(0)
	s_waitcnt lgkmcnt(0)
	v_mfma_f32_16x16x32_bf16 v[96:99], v[132:135], v[148:151], v[96:99]
	v_mfma_f32_16x16x32_bf16 v[92:95], v[140:143], v[148:151], v[92:95]
	v_mfma_f32_16x16x32_bf16 v[88:91], v[132:135], v[156:159], v[88:91]
	v_mfma_f32_16x16x32_bf16 v[84:87], v[140:143], v[156:159], v[84:87]
	v_mfma_f32_16x16x32_bf16 v[80:83], v[132:135], v[188:191], v[80:83]
	v_mfma_f32_16x16x32_bf16 v[76:79], v[140:143], v[188:191], v[76:79]
	v_mfma_f32_16x16x32_bf16 v[72:75], v[132:135], v[196:199], v[72:75]
	v_mfma_f32_16x16x32_bf16 v[68:71], v[140:143], v[196:199], v[68:71]
	v_mfma_f32_16x16x32_bf16 v[96:99], v[136:139], v[152:155], v[96:99]
	v_mfma_f32_16x16x32_bf16 v[92:95], v[144:147], v[152:155], v[92:95]
	v_mfma_f32_16x16x32_bf16 v[88:91], v[136:139], v[160:163], v[88:91]
	v_mfma_f32_16x16x32_bf16 v[84:87], v[144:147], v[160:163], v[84:87]
	v_mfma_f32_16x16x32_bf16 v[80:83], v[136:139], v[192:195], v[80:83]
	v_mfma_f32_16x16x32_bf16 v[76:79], v[144:147], v[192:195], v[76:79]
	v_mfma_f32_16x16x32_bf16 v[72:75], v[136:139], v[200:203], v[72:75]
	v_mfma_f32_16x16x32_bf16 v[68:71], v[144:147], v[200:203], v[68:71]
	s_barrier
	s_add_u32 s4, s4, 0x40080
	s_addc_u32 s5, s5, 0
	s_add_i32 s16, s16, s18
	v_lshl_add_u64 v[132:133], s[4:5], 0, v[172:173]
	s_mov_b32 m0, s16
	s_nop 0
	global_load_lds_dwordx4 v[132:133], off
	v_lshl_add_u64 v[132:133], s[4:5], 0, v[176:177]
	s_add_i32 m0, s16, 0x2000
	s_nop 0
	global_load_lds_dwordx4 v[132:133], off
	s_waitcnt vmcnt(6)
	s_barrier
	v_mfma_f32_16x16x32_bf16 v[32:35], v[204:207], v[148:151], v[32:35]
	v_mfma_f32_16x16x32_bf16 v[28:31], v[220:223], v[148:151], v[28:31]
	v_mfma_f32_16x16x32_bf16 v[24:27], v[204:207], v[156:159], v[24:27]
	v_mfma_f32_16x16x32_bf16 v[20:23], v[220:223], v[156:159], v[20:23]
	v_mfma_f32_16x16x32_bf16 v[16:19], v[204:207], v[188:191], v[16:19]
	v_mfma_f32_16x16x32_bf16 v[12:15], v[220:223], v[188:191], v[12:15]
	v_mfma_f32_16x16x32_bf16 v[8:11], v[204:207], v[196:199], v[8:11]
	v_mfma_f32_16x16x32_bf16 v[4:7], v[220:223], v[196:199], v[4:7]
	v_mfma_f32_16x16x32_bf16 v[32:35], v[208:211], v[152:155], v[32:35]
	v_mfma_f32_16x16x32_bf16 v[28:31], v[234:237], v[152:155], v[28:31]
	v_mfma_f32_16x16x32_bf16 v[24:27], v[208:211], v[160:163], v[24:27]
	v_mfma_f32_16x16x32_bf16 v[20:23], v[234:237], v[160:163], v[20:23]
	v_mfma_f32_16x16x32_bf16 v[16:19], v[208:211], v[192:195], v[16:19]
	v_mfma_f32_16x16x32_bf16 v[12:15], v[234:237], v[192:195], v[12:15]
	v_mfma_f32_16x16x32_bf16 v[8:11], v[208:211], v[200:203], v[8:11]
	v_mfma_f32_16x16x32_bf16 v[4:7], v[234:237], v[200:203], v[4:7]
	s_add_i32 s21, s21, 2
	s_add_u32 s0, s0, 0x100
	s_addc_u32 s1, s1, 0
	s_add_u32 s3, s3, 0x100
	s_addc_u32 s20, s20, 0
	s_cmp_gt_u32 s21, 13
	s_barrier
	s_cbranch_scc0 .LBB0_54
	s_branch .Lg1_kdone
.Lg1_metak:
	s_add_u32 s4, s0, 0xfffc0080
	s_addc_u32 s5, s1, -1
	s_add_i32 s36, 0, 0x10000
	v_add_u32_e32 v2, s36, v243
	ds_read_b128 v[132:135], v2
	ds_read_b128 v[136:139], v2 offset:1024
	ds_read_b128 v[140:143], v2 offset:2048
	ds_read_b128 v[144:147], v2 offset:3072
	s_cmp_eq_u32 s21, 12
	s_cselect_b32 s17, s51, s5
	s_cselect_b32 s16, s50, s4
	s_cselect_b32 s5, s7, s20
	s_cselect_b32 s4, s6, s3
	v_lshl_add_u64 v[168:169], s[0:1], 0, v[184:185]
	s_add_i32 m0, s23, 0xc000
	ds_read_b128 v[148:151], v245
	ds_read_b128 v[152:155], v245 offset:1024
	ds_read_b128 v[156:159], v245 offset:2048
	ds_read_b128 v[160:163], v245 offset:3072
	ds_read_b128 v[188:191], v245 offset:4096
	ds_read_b128 v[192:195], v245 offset:5120
	ds_read_b128 v[196:199], v245 offset:6144
	ds_read_b128 v[200:203], v245 offset:7168
	global_load_lds_dwordx4 v[168:169], off
	v_lshl_add_u64 v[168:169], s[0:1], 0, v[186:187]
	s_add_i32 m0, s23, 0xe000
	s_nop 0
	global_load_lds_dwordx4 v[168:169], off
	s_waitcnt lgkmcnt(8)
	s_barrier
	s_waitcnt lgkmcnt(0)
	s_waitcnt lgkmcnt(0)
	v_mfma_f32_16x16x32_bf16 v[128:131], v[132:135], v[148:151], 0
	v_mfma_f32_16x16x32_bf16 v[124:127], v[140:143], v[148:151], 0
	v_mfma_f32_16x16x32_bf16 v[120:123], v[132:135], v[156:159], 0
	v_mfma_f32_16x16x32_bf16 v[116:119], v[140:143], v[156:159], 0
	v_mfma_f32_16x16x32_bf16 v[112:115], v[132:135], v[188:191], 0
	v_mfma_f32_16x16x32_bf16 v[108:111], v[140:143], v[188:191], 0
	v_mfma_f32_16x16x32_bf16 v[104:107], v[132:135], v[196:199], 0
	v_mfma_f32_16x16x32_bf16 v[100:103], v[140:143], v[196:199], 0
	v_mfma_f32_16x16x32_bf16 v[128:131], v[136:139], v[152:155], v[128:131]
	v_mfma_f32_16x16x32_bf16 v[124:127], v[144:147], v[152:155], v[124:127]
	v_mfma_f32_16x16x32_bf16 v[120:123], v[136:139], v[160:163], v[120:123]
	v_mfma_f32_16x16x32_bf16 v[116:119], v[144:147], v[160:163], v[116:119]
	v_mfma_f32_16x16x32_bf16 v[112:115], v[136:139], v[192:195], v[112:115]
	v_mfma_f32_16x16x32_bf16 v[108:111], v[144:147], v[192:195], v[108:111]
	v_mfma_f32_16x16x32_bf16 v[104:107], v[136:139], v[200:203], v[104:107]
	v_mfma_f32_16x16x32_bf16 v[100:103], v[144:147], v[200:203], v[100:103]
	s_barrier
	s_add_i32 s40, 0, 0x14000
	s_add_i32 s36, s36, s18
	v_add_u32_e32 v2, s40, v243
	v_lshl_add_u64 v[168:169], s[4:5], 0, v[172:173]
	s_mov_b32 m0, s36
	ds_read_b128 v[204:207], v2
	ds_read_b128 v[208:211], v2 offset:1024
	ds_read_b128 v[234:237], v2 offset:2048
	ds_read_b128 v[220:223], v2 offset:3072
	global_load_lds_dwordx4 v[168:169], off
	v_lshl_add_u64 v[238:239], s[4:5], 0, v[176:177]
	s_add_i32 m0, s36, 0x2000
	s_nop 0
	global_load_lds_dwordx4 v[238:239], off
	s_barrier
	s_waitcnt lgkmcnt(0)
	s_waitcnt lgkmcnt(0)
	v_mfma_f32_16x16x32_bf16 v[64:67], v[204:207], v[148:151], 0
	v_mfma_f32_16x16x32_bf16 v[60:63], v[234:237], v[148:151], 0
	v_mfma_f32_16x16x32_bf16 v[56:59], v[204:207], v[156:159], 0
	v_mfma_f32_16x16x32_bf16 v[52:55], v[234:237], v[156:159], 0
	v_mfma_f32_16x16x32_bf16 v[48:51], v[204:207], v[188:191], 0
	v_mfma_f32_16x16x32_bf16 v[44:47], v[234:237], v[188:191], 0
	v_mfma_f32_16x16x32_bf16 v[40:43], v[204:207], v[196:199], 0
	v_mfma_f32_16x16x32_bf16 v[36:39], v[234:237], v[196:199], 0
	v_mfma_f32_16x16x32_bf16 v[64:67], v[208:211], v[152:155], v[64:67]
	v_mfma_f32_16x16x32_bf16 v[60:63], v[220:223], v[152:155], v[60:63]
	v_mfma_f32_16x16x32_bf16 v[56:59], v[208:211], v[160:163], v[56:59]
	v_mfma_f32_16x16x32_bf16 v[52:55], v[220:223], v[160:163], v[52:55]
	v_mfma_f32_16x16x32_bf16 v[48:51], v[208:211], v[192:195], v[48:51]
	v_mfma_f32_16x16x32_bf16 v[44:47], v[220:223], v[192:195], v[44:47]
	v_mfma_f32_16x16x32_bf16 v[40:43], v[208:211], v[200:203], v[40:43]
	v_mfma_f32_16x16x32_bf16 v[36:39], v[220:223], v[200:203], v[36:39]
	s_mov_b32 m0, s23
	v_lshl_add_u64 v[214:215], s[16:17], 0, v[0:1]
	s_barrier
	ds_read_b128 v[148:151], v245 offset:16384
	ds_read_b128 v[152:155], v245 offset:17408
	ds_read_b128 v[156:159], v245 offset:18432
	ds_read_b128 v[160:163], v245 offset:19456
	ds_read_b128 v[188:191], v245 offset:20480
	ds_read_b128 v[192:195], v245 offset:21504
	ds_read_b128 v[196:199], v245 offset:22528
	ds_read_b128 v[200:203], v245 offset:23552
	global_load_lds_dwordx4 v[214:215], off
	v_lshl_add_u64 v[224:225], s[16:17], 0, v[174:175]
	s_mov_b32 m0, s26
	s_nop 0
	global_load_lds_dwordx4 v[224:225], off
	s_barrier
	s_waitcnt lgkmcnt(0)
	s_waitcnt lgkmcnt(0)
	s_barrier
	s_add_u32 s36, s4, 0x40000
	s_addc_u32 s37, s5, 0
	s_add_i32 s40, s40, s18
	v_lshl_add_u64 v[132:133], s[36:37], 0, v[172:173]
	s_mov_b32 m0, s40
	s_nop 0
	global_load_lds_dwordx4 v[132:133], off
	v_lshl_add_u64 v[132:133], s[36:37], 0, v[176:177]
	s_add_i32 m0, s40, 0x2000
	s_nop 0
	global_load_lds_dwordx4 v[132:133], off
	s_waitcnt vmcnt(6)
	s_barrier
	s_add_i32 s36, 0, 0x18000
	v_add_u32_e32 v2, s36, v243
	s_barrier
	ds_read_b128 v[132:135], v2
	ds_read_b128 v[136:139], v2 offset:1024
	ds_read_b128 v[140:143], v2 offset:2048
	ds_read_b128 v[144:147], v2 offset:3072
	s_add_u32 s16, s16, 0x40000
	s_addc_u32 s17, s17, 0
	s_mov_b32 m0, s27
	v_lshl_add_u64 v[204:205], s[16:17], 0, v[0:1]
	ds_read_b128 v[148:151], v245 offset:32768
	ds_read_b128 v[152:155], v245 offset:33792
	ds_read_b128 v[156:159], v245 offset:34816
	ds_read_b128 v[160:163], v245 offset:35840
	ds_read_b128 v[188:191], v245 offset:36864
	ds_read_b128 v[192:195], v245 offset:37888
	ds_read_b128 v[196:199], v245 offset:38912
	ds_read_b128 v[200:203], v245 offset:39936
	global_load_lds_dwordx4 v[204:205], off
	v_lshl_add_u64 v[204:205], s[16:17], 0, v[174:175]
	s_mov_b32 m0, s30
	s_nop 0
	global_load_lds_dwordx4 v[204:205], off
	s_waitcnt lgkmcnt(8)
	s_barrier
	s_waitcnt lgkmcnt(0)
	s_waitcnt lgkmcnt(0)
	v_mfma_f32_16x16x32_bf16 v[128:131], v[132:135], v[148:151], v[128:131]
	v_mfma_f32_16x16x32_bf16 v[124:127], v[140:143], v[148:151], v[124:127]
	v_mfma_f32_16x16x32_bf16 v[120:123], v[132:135], v[156:159], v[120:123]
	v_mfma_f32_16x16x32_bf16 v[116:119], v[140:143], v[156:159], v[116:119]
	v_mfma_f32_16x16x32_bf16 v[112:115], v[132:135], v[188:191], v[112:115]
	v_mfma_f32_16x16x32_bf16 v[108:111], v[140:143], v[188:191], v[108:111]
	v_mfma_f32_16x16x32_bf16 v[104:107], v[132:135], v[196:199], v[104:107]
	v_mfma_f32_16x16x32_bf16 v[100:103], v[140:143], v[196:199], v[100:103]
	v_mfma_f32_16x16x32_bf16 v[128:131], v[136:139], v[152:155], v[128:131]
	v_mfma_f32_16x16x32_bf16 v[124:127], v[144:147], v[152:155], v[124:127]
	v_mfma_f32_16x16x32_bf16 v[120:123], v[136:139], v[160:163], v[120:123]
	v_mfma_f32_16x16x32_bf16 v[116:119], v[144:147], v[160:163], v[116:119]
	v_mfma_f32_16x16x32_bf16 v[112:115], v[136:139], v[192:195], v[112:115]
	v_mfma_f32_16x16x32_bf16 v[108:111], v[144:147], v[192:195], v[108:111]
	v_mfma_f32_16x16x32_bf16 v[104:107], v[136:139], v[200:203], v[104:107]
	v_mfma_f32_16x16x32_bf16 v[100:103], v[144:147], v[200:203], v[100:103]
	s_barrier
	s_add_i32 s16, 0, 0x1c000
	s_add_i32 s17, s36, s18
	v_add_u32_e32 v2, s16, v243
	v_lshl_add_u64 v[168:169], v[168:169], 0, s[28:29]
	s_mov_b32 m0, s17
	ds_read_b128 v[204:207], v2
	ds_read_b128 v[208:211], v2 offset:1024
	ds_read_b128 v[220:223], v2 offset:2048
	ds_read_b128 v[234:237], v2 offset:3072
	global_load_lds_dwordx4 v[168:169], off
	v_lshl_add_u64 v[168:169], v[238:239], 0, s[28:29]
	s_add_i32 m0, s17, 0x2000
	s_nop 0
	global_load_lds_dwordx4 v[168:169], off
	s_barrier
	s_waitcnt lgkmcnt(0)
	s_waitcnt lgkmcnt(0)
	v_mfma_f32_16x16x32_bf16 v[64:67], v[204:207], v[148:151], v[64:67]
	v_mfma_f32_16x16x32_bf16 v[60:63], v[220:223], v[148:151], v[60:63]
	v_mfma_f32_16x16x32_bf16 v[56:59], v[204:207], v[156:159], v[56:59]
	v_mfma_f32_16x16x32_bf16 v[52:55], v[220:223], v[156:159], v[52:55]
	v_mfma_f32_16x16x32_bf16 v[48:51], v[204:207], v[188:191], v[48:51]
	v_mfma_f32_16x16x32_bf16 v[44:47], v[220:223], v[188:191], v[44:47]
	v_mfma_f32_16x16x32_bf16 v[40:43], v[204:207], v[196:199], v[40:43]
	v_mfma_f32_16x16x32_bf16 v[36:39], v[220:223], v[196:199], v[36:39]
	v_mfma_f32_16x16x32_bf16 v[64:67], v[208:211], v[152:155], v[64:67]
	v_mfma_f32_16x16x32_bf16 v[60:63], v[234:237], v[152:155], v[60:63]
	v_mfma_f32_16x16x32_bf16 v[56:59], v[208:211], v[160:163], v[56:59]
	v_mfma_f32_16x16x32_bf16 v[52:55], v[234:237], v[160:163], v[52:55]
	v_mfma_f32_16x16x32_bf16 v[48:51], v[208:211], v[192:195], v[48:51]
	v_mfma_f32_16x16x32_bf16 v[44:47], v[234:237], v[192:195], v[44:47]
	v_mfma_f32_16x16x32_bf16 v[40:43], v[208:211], v[200:203], v[40:43]
	v_mfma_f32_16x16x32_bf16 v[36:39], v[234:237], v[200:203], v[36:39]
	s_mov_b32 m0, s76
	v_lshl_add_u64 v[168:169], v[214:215], 0, s[28:29]
	s_barrier
	ds_read_b128 v[148:151], v245 offset:49152
	ds_read_b128 v[152:155], v245 offset:50176
	ds_read_b128 v[156:159], v245 offset:51200
	ds_read_b128 v[160:163], v245 offset:52224
	ds_read_b128 v[188:191], v245 offset:53248
	ds_read_b128 v[192:195], v245 offset:54272
	ds_read_b128 v[196:199], v245 offset:55296
	ds_read_b128 v[200:203], v245 offset:56320
	global_load_lds_dwordx4 v[168:169], off
	v_lshl_add_u64 v[168:169], v[224:225], 0, s[28:29]
	s_mov_b32 m0, s77
	s_nop 0
	global_load_lds_dwordx4 v[168:169], off
	s_barrier
	s_waitcnt lgkmcnt(0)
	s_waitcnt lgkmcnt(0)
	s_barrier
	s_add_u32 s4, s4, 0x40080
	s_addc_u32 s5, s5, 0
	s_add_i32 s16, s16, s18
	v_lshl_add_u64 v[132:133], s[4:5], 0, v[172:173]
	s_mov_b32 m0, s16
	s_nop 0
	global_load_lds_dwordx4 v[132:133], off
	v_lshl_add_u64 v[132:133], s[4:5], 0, v[176:177]
	s_add_i32 m0, s16, 0x2000
	s_nop 0
	global_load_lds_dwordx4 v[132:133], off
	s_waitcnt vmcnt(6)
	s_barrier
	s_add_i32 s21, s21, 2
	s_add_u32 s0, s0, 0x100
	s_addc_u32 s1, s1, 0
	s_add_u32 s3, s3, 0x100
	s_addc_u32 s20, s20, 0
	s_cmp_gt_u32 s21, 13
	s_barrier
.Lg1_metaloop:
	s_add_u32 s4, s0, 0xfffc0080
	s_addc_u32 s5, s1, -1
	s_add_i32 s36, 0, 0x10000
	v_add_u32_e32 v2, s36, v243
	ds_read_b128 v[132:135], v2
	ds_read_b128 v[136:139], v2 offset:1024
	ds_read_b128 v[140:143], v2 offset:2048
	ds_read_b128 v[144:147], v2 offset:3072
	s_cmp_eq_u32 s21, 12
	s_cselect_b32 s17, s51, s5
	s_cselect_b32 s16, s50, s4
	s_cselect_b32 s5, s7, s20
	s_cselect_b32 s4, s6, s3
	v_lshl_add_u64 v[168:169], s[0:1], 0, v[184:185]
	s_add_i32 m0, s23, 0xc000
	ds_read_b128 v[148:151], v245
	ds_read_b128 v[152:155], v245 offset:1024
	ds_read_b128 v[156:159], v245 offset:2048
	ds_read_b128 v[160:163], v245 offset:3072
	ds_read_b128 v[188:191], v245 offset:4096
	ds_read_b128 v[192:195], v245 offset:5120
	ds_read_b128 v[196:199], v245 offset:6144
	ds_read_b128 v[200:203], v245 offset:7168
	global_load_lds_dwordx4 v[168:169], off
	v_lshl_add_u64 v[168:169], s[0:1], 0, v[186:187]
	s_add_i32 m0, s23, 0xe000
	s_nop 0
	global_load_lds_dwordx4 v[168:169], off
	s_waitcnt lgkmcnt(8)
	s_barrier
	s_waitcnt lgkmcnt(0)
	s_waitcnt lgkmcnt(0)
	v_mfma_f32_16x16x32_bf16 v[128:131], v[132:135], v[148:151], v[128:131]
	v_mfma_f32_16x16x32_bf16 v[124:127], v[140:143], v[148:151], v[124:127]
	v_mfma_f32_16x16x32_bf16 v[120:123], v[132:135], v[156:159], v[120:123]
	v_mfma_f32_16x16x32_bf16 v[116:119], v[140:143], v[156:159], v[116:119]
	v_mfma_f32_16x16x32_bf16 v[112:115], v[132:135], v[188:191], v[112:115]
	v_mfma_f32_16x16x32_bf16 v[108:111], v[140:143], v[188:191], v[108:111]
	v_mfma_f32_16x16x32_bf16 v[104:107], v[132:135], v[196:199], v[104:107]
	v_mfma_f32_16x16x32_bf16 v[100:103], v[140:143], v[196:199], v[100:103]
	v_mfma_f32_16x16x32_bf16 v[128:131], v[136:139], v[152:155], v[128:131]
	v_mfma_f32_16x16x32_bf16 v[124:127], v[144:147], v[152:155], v[124:127]
	v_mfma_f32_16x16x32_bf16 v[120:123], v[136:139], v[160:163], v[120:123]
	v_mfma_f32_16x16x32_bf16 v[116:119], v[144:147], v[160:163], v[116:119]
	v_mfma_f32_16x16x32_bf16 v[112:115], v[136:139], v[192:195], v[112:115]
	v_mfma_f32_16x16x32_bf16 v[108:111], v[144:147], v[192:195], v[108:111]
	v_mfma_f32_16x16x32_bf16 v[104:107], v[136:139], v[200:203], v[104:107]
	v_mfma_f32_16x16x32_bf16 v[100:103], v[144:147], v[200:203], v[100:103]
	s_barrier
	s_add_i32 s40, 0, 0x14000
	s_add_i32 s36, s36, s18
	v_add_u32_e32 v2, s40, v243
	v_lshl_add_u64 v[168:169], s[4:5], 0, v[172:173]
	s_mov_b32 m0, s36
	ds_read_b128 v[204:207], v2
	ds_read_b128 v[208:211], v2 offset:1024
	ds_read_b128 v[234:237], v2 offset:2048
	ds_read_b128 v[220:223], v2 offset:3072
	global_load_lds_dwordx4 v[168:169], off
	v_lshl_add_u64 v[238:239], s[4:5], 0, v[176:177]
	s_add_i32 m0, s36, 0x2000
	s_nop 0
	global_load_lds_dwordx4 v[238:239], off
	s_barrier
	s_waitcnt lgkmcnt(0)
	s_waitcnt lgkmcnt(0)
	v_mfma_f32_16x16x32_bf16 v[64:67], v[204:207], v[148:151], v[64:67]
	v_mfma_f32_16x16x32_bf16 v[60:63], v[234:237], v[148:151], v[60:63]
	v_mfma_f32_16x16x32_bf16 v[56:59], v[204:207], v[156:159], v[56:59]
	v_mfma_f32_16x16x32_bf16 v[52:55], v[234:237], v[156:159], v[52:55]
	v_mfma_f32_16x16x32_bf16 v[48:51], v[204:207], v[188:191], v[48:51]
	v_mfma_f32_16x16x32_bf16 v[44:47], v[234:237], v[188:191], v[44:47]
	v_mfma_f32_16x16x32_bf16 v[40:43], v[204:207], v[196:199], v[40:43]
	v_mfma_f32_16x16x32_bf16 v[36:39], v[234:237], v[196:199], v[36:39]
	v_mfma_f32_16x16x32_bf16 v[64:67], v[208:211], v[152:155], v[64:67]
	v_mfma_f32_16x16x32_bf16 v[60:63], v[220:223], v[152:155], v[60:63]
	v_mfma_f32_16x16x32_bf16 v[56:59], v[208:211], v[160:163], v[56:59]
	v_mfma_f32_16x16x32_bf16 v[52:55], v[220:223], v[160:163], v[52:55]
	v_mfma_f32_16x16x32_bf16 v[48:51], v[208:211], v[192:195], v[48:51]
	v_mfma_f32_16x16x32_bf16 v[44:47], v[220:223], v[192:195], v[44:47]
	v_mfma_f32_16x16x32_bf16 v[40:43], v[208:211], v[200:203], v[40:43]
	v_mfma_f32_16x16x32_bf16 v[36:39], v[220:223], v[200:203], v[36:39]
	s_mov_b32 m0, s23
	v_lshl_add_u64 v[214:215], s[16:17], 0, v[0:1]
	s_barrier
	ds_read_b128 v[148:151], v245 offset:16384
	ds_read_b128 v[152:155], v245 offset:17408
	ds_read_b128 v[156:159], v245 offset:18432
	ds_read_b128 v[160:163], v245 offset:19456
	ds_read_b128 v[188:191], v245 offset:20480
	ds_read_b128 v[192:195], v245 offset:21504
	ds_read_b128 v[196:199], v245 offset:22528
	ds_read_b128 v[200:203], v245 offset:23552
	global_load_lds_dwordx4 v[214:215], off
	v_lshl_add_u64 v[224:225], s[16:17], 0, v[174:175]
	s_mov_b32 m0, s26
	s_nop 0
	global_load_lds_dwordx4 v[224:225], off
	s_barrier
	s_waitcnt lgkmcnt(0)
	s_waitcnt lgkmcnt(0)
	s_barrier
	s_add_u32 s36, s4, 0x40000
	s_addc_u32 s37, s5, 0
	s_add_i32 s40, s40, s18
	v_lshl_add_u64 v[132:133], s[36:37], 0, v[172:173]
	s_mov_b32 m0, s40
	s_nop 0
	global_load_lds_dwordx4 v[132:133], off
	v_lshl_add_u64 v[132:133], s[36:37], 0, v[176:177]
	s_add_i32 m0, s40, 0x2000
	s_nop 0
	global_load_lds_dwordx4 v[132:133], off
	s_waitcnt vmcnt(6)
	s_barrier
	s_add_i32 s36, 0, 0x18000
	v_add_u32_e32 v2, s36, v243
	s_barrier
	ds_read_b128 v[132:135], v2
	ds_read_b128 v[136:139], v2 offset:1024
	ds_read_b128 v[140:143], v2 offset:2048
	ds_read_b128 v[144:147], v2 offset:3072
	s_add_u32 s16, s16, 0x40000
	s_addc_u32 s17, s17, 0
	s_mov_b32 m0, s27
	v_lshl_add_u64 v[204:205], s[16:17], 0, v[0:1]
	ds_read_b128 v[148:151], v245 offset:32768
	ds_read_b128 v[152:155], v245 offset:33792
	ds_read_b128 v[156:159], v245 offset:34816
	ds_read_b128 v[160:163], v245 offset:35840
	ds_read_b128 v[188:191], v245 offset:36864
	ds_read_b128 v[192:195], v245 offset:37888
	ds_read_b128 v[196:199], v245 offset:38912
	ds_read_b128 v[200:203], v245 offset:39936
	global_load_lds_dwordx4 v[204:205], off
	v_lshl_add_u64 v[204:205], s[16:17], 0, v[174:175]
	s_mov_b32 m0, s30
	s_nop 0
	global_load_lds_dwordx4 v[204:205], off
	s_waitcnt lgkmcnt(8)
	s_barrier
	s_waitcnt lgkmcnt(0)
	s_waitcnt lgkmcnt(0)
	v_mfma_f32_16x16x32_bf16 v[128:131], v[132:135], v[148:151], v[128:131]
	v_mfma_f32_16x16x32_bf16 v[124:127], v[140:143], v[148:151], v[124:127]
	v_mfma_f32_16x16x32_bf16 v[120:123], v[132:135], v[156:159], v[120:123]
	v_mfma_f32_16x16x32_bf16 v[116:119], v[140:143], v[156:159], v[116:119]
	v_mfma_f32_16x16x32_bf16 v[112:115], v[132:135], v[188:191], v[112:115]
	v_mfma_f32_16x16x32_bf16 v[108:111], v[140:143], v[188:191], v[108:111]
	v_mfma_f32_16x16x32_bf16 v[104:107], v[132:135], v[196:199], v[104:107]
	v_mfma_f32_16x16x32_bf16 v[100:103], v[140:143], v[196:199], v[100:103]
	v_mfma_f32_16x16x32_bf16 v[128:131], v[136:139], v[152:155], v[128:131]
	v_mfma_f32_16x16x32_bf16 v[124:127], v[144:147], v[152:155], v[124:127]
	v_mfma_f32_16x16x32_bf16 v[120:123], v[136:139], v[160:163], v[120:123]
	v_mfma_f32_16x16x32_bf16 v[116:119], v[144:147], v[160:163], v[116:119]
	v_mfma_f32_16x16x32_bf16 v[112:115], v[136:139], v[192:195], v[112:115]
	v_mfma_f32_16x16x32_bf16 v[108:111], v[144:147], v[192:195], v[108:111]
	v_mfma_f32_16x16x32_bf16 v[104:107], v[136:139], v[200:203], v[104:107]
	v_mfma_f32_16x16x32_bf16 v[100:103], v[144:147], v[200:203], v[100:103]
	s_barrier
	s_add_i32 s16, 0, 0x1c000
	s_add_i32 s17, s36, s18
	v_add_u32_e32 v2, s16, v243
	v_lshl_add_u64 v[168:169], v[168:169], 0, s[28:29]
	s_mov_b32 m0, s17
	ds_read_b128 v[204:207], v2
	ds_read_b128 v[208:211], v2 offset:1024
	ds_read_b128 v[220:223], v2 offset:2048
	ds_read_b128 v[234:237], v2 offset:3072
	global_load_lds_dwordx4 v[168:169], off
	v_lshl_add_u64 v[168:169], v[238:239], 0, s[28:29]
	s_add_i32 m0, s17, 0x2000
	s_nop 0
	global_load_lds_dwordx4 v[168:169], off
	s_barrier
	s_waitcnt lgkmcnt(0)
	s_waitcnt lgkmcnt(0)
	v_mfma_f32_16x16x32_bf16 v[64:67], v[204:207], v[148:151], v[64:67]
	v_mfma_f32_16x16x32_bf16 v[60:63], v[220:223], v[148:151], v[60:63]
	v_mfma_f32_16x16x32_bf16 v[56:59], v[204:207], v[156:159], v[56:59]
	v_mfma_f32_16x16x32_bf16 v[52:55], v[220:223], v[156:159], v[52:55]
	v_mfma_f32_16x16x32_bf16 v[48:51], v[204:207], v[188:191], v[48:51]
	v_mfma_f32_16x16x32_bf16 v[44:47], v[220:223], v[188:191], v[44:47]
	v_mfma_f32_16x16x32_bf16 v[40:43], v[204:207], v[196:199], v[40:43]
	v_mfma_f32_16x16x32_bf16 v[36:39], v[220:223], v[196:199], v[36:39]
	v_mfma_f32_16x16x32_bf16 v[64:67], v[208:211], v[152:155], v[64:67]
	v_mfma_f32_16x16x32_bf16 v[60:63], v[234:237], v[152:155], v[60:63]
	v_mfma_f32_16x16x32_bf16 v[56:59], v[208:211], v[160:163], v[56:59]
	v_mfma_f32_16x16x32_bf16 v[52:55], v[234:237], v[160:163], v[52:55]
	v_mfma_f32_16x16x32_bf16 v[48:51], v[208:211], v[192:195], v[48:51]
	v_mfma_f32_16x16x32_bf16 v[44:47], v[234:237], v[192:195], v[44:47]
	v_mfma_f32_16x16x32_bf16 v[40:43], v[208:211], v[200:203], v[40:43]
	v_mfma_f32_16x16x32_bf16 v[36:39], v[234:237], v[200:203], v[36:39]
	s_mov_b32 m0, s76
	v_lshl_add_u64 v[168:169], v[214:215], 0, s[28:29]
	s_barrier
	ds_read_b128 v[148:151], v245 offset:49152
	ds_read_b128 v[152:155], v245 offset:50176
	ds_read_b128 v[156:159], v245 offset:51200
	ds_read_b128 v[160:163], v245 offset:52224
	ds_read_b128 v[188:191], v245 offset:53248
	ds_read_b128 v[192:195], v245 offset:54272
	ds_read_b128 v[196:199], v245 offset:55296
	ds_read_b128 v[200:203], v245 offset:56320
	global_load_lds_dwordx4 v[168:169], off
	v_lshl_add_u64 v[168:169], v[224:225], 0, s[28:29]
	s_mov_b32 m0, s77
	s_nop 0
	global_load_lds_dwordx4 v[168:169], off
	s_barrier
	s_waitcnt lgkmcnt(0)
	s_waitcnt lgkmcnt(0)
	s_barrier
	s_add_u32 s4, s4, 0x40080
	s_addc_u32 s5, s5, 0
	s_add_i32 s16, s16, s18
	v_lshl_add_u64 v[132:133], s[4:5], 0, v[172:173]
	s_mov_b32 m0, s16
	s_nop 0
	global_load_lds_dwordx4 v[132:133], off
	v_lshl_add_u64 v[132:133], s[4:5], 0, v[176:177]
	s_add_i32 m0, s16, 0x2000
	s_nop 0
	global_load_lds_dwordx4 v[132:133], off
	s_waitcnt vmcnt(6)
	s_barrier
	s_add_i32 s21, s21, 2
	s_add_u32 s0, s0, 0x100
	s_addc_u32 s1, s1, 0
	s_add_u32 s3, s3, 0x100
	s_addc_u32 s20, s20, 0
	s_cmp_gt_u32 s21, 13
	s_barrier
	s_cbranch_scc0 .Lg1_metaloop
.Lg1_kdone:
	s_lshl_b32 s74, s2, 8
	s_cmp_lt_i32 s2, 2
	s_mov_b32 s2, 0
	s_movk_i32 s20, 0x4000
	s_cbranch_scc1 .LBB0_60
	s_cmpk_lt_u32 s74, 0x400
	s_mov_b32 s2, 1
	s_cbranch_scc1 .LBB0_60
	s_cmpk_lt_u32 s74, 0x800
	s_mov_b32 s2, 2
	s_cbranch_scc1 .LBB0_60
	s_cmpk_lt_u32 s74, 0xc00
	s_mov_b32 s2, 3
	s_cbranch_scc1 .LBB0_60
	s_cmpk_lt_u32 s74, 0x1300
	s_cselect_b32 s0, 7, 8
	s_cmpk_gt_u32 s74, 0xeff
	s_cselect_b32 s0, s0, 6
	s_cmpk_gt_u32 s74, 0xe7f
	s_cselect_b32 s0, s0, 5
	s_cmpk_gt_u32 s74, 0xdff
	s_cselect_b32 s2, s0, 4
